# fixup-tile-0-batched-loads
# baseline (speedup 1.0000x reference)
; template <int MODE>
; __device__ void fixup_mine(const pg8::StaticOrder& S, const float* cw, int C, int voff, int nch, const float* PART, const float* TAIL, bf16_t* O, int ldo, const bf16_t* BG) {
;     pg8::Unit u; int last_pm = -1;
;     for (int i = 0; S.next(i, u); ++i) { if (u.pm != last_pm) fixup_tile<MODE>(u.pm, cw, C, voff, nch, PART, TAIL, O, ldo, BG); last_pm = u.pm; }
; __global__ void __launch_bounds__(512, 2) fwd_megakernel(Params p_unused) {
;     ...
;             pg8::Gemm g{WSP(bf16_t, WS_ACT), WSP(bf16_t, WS_WDOWN) + (size_t)l * D * FF, M, D, FF, FF, NOGRP, 0}; pg8::StaticOrder S; S.init(M, D, G, bid);
;             fixup_mine<0>(S, q->fconv_w + (size_t)l * 3 * NUP, NUP, FF, FF, WSP(float, WS_PART), WSP(float, WS_TAIL), WSP(bf16_t, WS_ACT), FF, nullptr);
.LBB0_820:
	s_mov_b32 s0, 0
	s_ashr_i32 s1, s0, 31
	s_add_u32 s0, s96, s0
	s_addc_u32 s1, s97, s1
	s_load_dwordx2 s[8:9], s[0:1], 0x90
	s_nop 0
	s_load_dwordx2 s[0:1], s[0:1], 0x68
	s_mov_b32 s24, -1
	s_mov_b32 s21, 0
	s_waitcnt lgkmcnt(0)
	s_add_u32 s10, s8, 0x12630000
	s_addc_u32 s11, s9, 0
	s_add_u32 s52, s0, s88
	s_addc_u32 s53, s1, 0
	s_add_u32 s54, s8, 0x28630000
	s_addc_u32 s55, s9, 0
	s_add_u32 s0, s8, 0x29130000
	s_addc_u32 s1, s9, 0
	s_add_u32 s56, s52, 0xb000
	s_addc_u32 s57, s53, 0
	s_branch .LBB0_824
.LBB0_822:
	s_add_i32 s21, s21, 1
	s_mov_b64 s[6:7], 0

;     __device__ bool next(int i, Unit& u) const {
;     ...
;         int wgid = (int)L; { const int q = nwg / NXCD, r = nwg % NXCD, xcd = wgid % NXCD, off = wgid / NXCD; wgid = (xcd < r ? xcd * (q + 1) : r * (q + 1) + (xcd - r) * q) + off; }
;         const int nig = WGM * nN, gid = wgid / nig, fm = gid * WGM, gsz = (nM - fm) < WGM ? (nM - fm) : WGM;
;         u.pm = fm + ((wgid % nig) % gsz); u.pn = (wgid % nig) / gsz; return true;
; template <int MODE>
; __device__ void fixup_tile(int pm, const float* cw, int C, int voff, int nch, const float* PART, const float* TAIL, bf16_t* O, int ldo, const bf16_t* BG) {
;     ...
;     for (int i = tid; i < 2 * nq; i += 512) {
;         const int r = i / nq, ch = (i - r * nq) * 4;
;         const size_t row = (size_t)pm * 256 + r;
;         f32x4 val[2];
; #pragma unroll
;         for (int s = 0; s < (MODE == 0 ? 2 : 1); ++s) {
;             const int co = (s ? voff : 0) + ch;
;             f32x4 a = *(const f32x4*)(PART + (size_t)(pm * 2 + r) * C + co);
;             if ((pm & 63) != 0) {
;                 const f32x4 t1 = *(const f32x4*)(TAIL + (size_t)((pm - 1) * 2 + 1) * C + co);
;                 const f32x4 w0 = *(const f32x4*)(cw + co);
;                 if (r == 0) { const f32x4 t2 = *(const f32x4*)(TAIL + (size_t)((pm - 1) * 2 + 0) * C + co); const f32x4 w1 = *(const f32x4*)(cw + C + co); a += w1 * t1 + w0 * t2; }
;                 else a += w0 * t1;
;             }
;             val[s] = a;
;         }
.LBB0_829:
	s_ashr_i32 s4, s6, 3
	s_add_i32 s4, s22, s4
	s_ashr_i32 s5, s4, 31
	s_lshr_b32 s5, s5, 26
	s_add_i32 s5, s4, s5
	s_ashr_i32 s6, s5, 6
	s_lshl_b32 s6, s6, 3
	s_sub_i32 s7, 0x80, s6
	s_min_i32 s7, s7, 8
	s_abs_i32 s7, s7
	v_cvt_f32_u32_e32 v0, s7
	s_sub_i32 s22, 0, s7
	s_andn2_b32 s5, s5, 63
	s_sub_i32 s4, s4, s5
	v_rcp_iflag_f32_e32 v0, v0
	s_ashr_i32 s5, s4, 31
	s_abs_i32 s4, s4
	v_mul_f32_e32 v0, 0x4f7ffffe, v0
	v_cvt_u32_f32_e32 v0, v0
	s_nop 0
	v_readfirstlane_b32 s25, v0
	s_mul_i32 s22, s22, s25
	s_mul_hi_u32 s22, s25, s22
	s_add_i32 s25, s25, s22
	s_mul_hi_u32 s22, s4, s25
	s_mul_i32 s22, s22, s7
	s_sub_i32 s4, s4, s22
	s_sub_i32 s22, s4, s7
	s_cmp_ge_u32 s4, s7
	s_cselect_b32 s4, s22, s4
	s_sub_i32 s22, s4, s7
	s_cmp_ge_u32 s4, s7
	s_cselect_b32 s4, s22, s4
	s_xor_b32 s4, s4, s5
	s_sub_i32 s4, s4, s5
	s_add_i32 s22, s6, s4
	s_cmp_eq_u32 s22, s24
	s_cbranch_scc1 .LBB0_822
	s_lshl_b32 s24, s22, 1
	s_and_b32 s4, s22, 63
	s_cmp_lg_u32 s4, 0
	s_cselect_b64 s[60:61], -1, 0
	v_lshlrev_b32_e32 v12, 4, v235
	s_mul_i32 s4, s22, 0x16000
	s_add_u32 s58, s54, s4
	s_addc_u32 s59, s55, 0
	s_add_u32 s66, s58, 0xb000
	s_addc_u32 s67, s59, 0
	s_add_i32 s5, s4, 0xffff5000
	s_add_u32 s62, s0, s5
	s_addc_u32 s63, s1, 0
	s_add_i32 s5, s4, 0xfffea000
	s_add_u32 s64, s0, s5
	s_addc_u32 s65, s1, 0
	s_mul_i32 s4, s22, 0x2c0000
	s_add_u32 s68, s10, s4
	s_addc_u32 s69, s11, 0
	v_readfirstlane_b32 s25, v235
	v_add_u32_e32 v13, 0x5800, v12
	v_add_u32_e32 v14, 0x2000, v12
	v_add_u32_e32 v15, 0x7800, v12
	v_add_u32_e32 v16, 0x4000, v12
	v_add_u32_e32 v17, 0x9800, v12
	s_cmpk_lt_u32 s25, 0x180
	s_cselect_b64 s[26:27], -1, 0
	global_load_dwordx4 v[20:23], v12, s[58:59]
	global_load_dwordx4 v[24:27], v12, s[66:67]
	global_load_dwordx4 v[44:47], v13, s[58:59]
	global_load_dwordx4 v[48:51], v13, s[66:67]
	global_load_dwordx4 v[68:71], v14, s[58:59]
	global_load_dwordx4 v[72:75], v14, s[66:67]
	global_load_dwordx4 v[92:95], v15, s[58:59]
	global_load_dwordx4 v[96:99], v15, s[66:67]
	s_andn2_b64 vcc, exec, s[26:27]
	s_cbranch_vccnz .Lfx0_l2done
	global_load_dwordx4 v[116:119], v16, s[58:59]
	global_load_dwordx4 v[120:123], v16, s[66:67]
	global_load_dwordx4 v[140:143], v17, s[58:59]
	global_load_dwordx4 v[144:147], v17, s[66:67]
.Lfx0_l2done:
	s_andn2_b64 vcc, exec, s[60:61]
	s_cbranch_vccnz .Lfx0_hdone
	global_load_dwordx4 v[28:31], v12, s[62:63]
	global_load_dwordx4 v[32:35], v12, s[64:65]
	global_load_dwordx4 v[36:39], v12, s[52:53]
	global_load_dwordx4 v[40:43], v12, s[56:57]
	global_load_dwordx4 v[52:55], v13, s[62:63]
	global_load_dwordx4 v[56:59], v13, s[64:65]
	global_load_dwordx4 v[60:63], v13, s[52:53]
	global_load_dwordx4 v[64:67], v13, s[56:57]
	global_load_dwordx4 v[76:79], v14, s[62:63]
	global_load_dwordx4 v[80:83], v14, s[64:65]
	global_load_dwordx4 v[84:87], v14, s[52:53]
	global_load_dwordx4 v[88:91], v14, s[56:57]
	global_load_dwordx4 v[100:103], v15, s[62:63]
	global_load_dwordx4 v[104:107], v15, s[64:65]
	global_load_dwordx4 v[108:111], v15, s[52:53]
	global_load_dwordx4 v[112:115], v15, s[56:57]
	s_andn2_b64 vcc, exec, s[26:27]
	s_cbranch_vccnz .Lfx0_hdone
	global_load_dwordx4 v[124:127], v16, s[62:63]
	global_load_dwordx4 v[128:131], v16, s[64:65]
	global_load_dwordx4 v[132:135], v16, s[52:53]
	global_load_dwordx4 v[136:139], v16, s[56:57]
	global_load_dwordx4 v[148:151], v17, s[62:63]
	global_load_dwordx4 v[152:155], v17, s[64:65]
	global_load_dwordx4 v[156:159], v17, s[52:53]
	global_load_dwordx4 v[160:163], v17, s[56:57]
.Lfx0_hdone:
	v_mov_b32_e32 v167, v235
	v_and_b32_e32 v168, -16, v167
	v_and_b32_e32 v169, 8, v167
	v_and_b32_e32 v167, 7, v167
	v_lshlrev_b32_e32 v168, 10, v168
	v_lshlrev_b32_e32 v169, 7, v169
	v_lshlrev_b32_e32 v167, 3, v167
	v_or3_b32 v164, v168, v169, v167
	v_add_u32_e32 v167, 512, v235
	v_and_b32_e32 v168, -16, v167
	v_and_b32_e32 v169, 8, v167
	v_and_b32_e32 v167, 7, v167
	v_lshlrev_b32_e32 v168, 10, v168
	v_lshlrev_b32_e32 v169, 7, v169
	v_lshlrev_b32_e32 v167, 3, v167
	v_or3_b32 v165, v168, v169, v167
	v_add_u32_e32 v167, 1024, v235
	v_and_b32_e32 v168, -16, v167
	v_and_b32_e32 v169, 8, v167
	v_and_b32_e32 v167, 7, v167
	v_lshlrev_b32_e32 v168, 10, v168
	v_lshlrev_b32_e32 v169, 7, v169
	v_lshlrev_b32_e32 v167, 3, v167
	v_or3_b32 v166, v168, v169, v167
	s_waitcnt vmcnt(0)
	s_andn2_b64 vcc, exec, s[60:61]
	s_cbranch_vccnz .Lfx0_nohalo
	v_pk_mul_f32 v[40:41], v[28:29], v[40:41]
	v_pk_mul_f32 v[42:43], v[30:31], v[42:43]
	v_pk_fma_f32 v[40:41], v[36:37], v[32:33], v[40:41]
	v_pk_fma_f32 v[42:43], v[38:39], v[34:35], v[42:43]
	v_pk_mul_f32 v[28:29], v[28:29], v[36:37]
	v_pk_mul_f32 v[30:31], v[30:31], v[38:39]
	v_pk_add_f32 v[20:21], v[20:21], v[40:41]
	v_pk_add_f32 v[22:23], v[22:23], v[42:43]
	v_pk_add_f32 v[24:25], v[24:25], v[28:29]
	v_pk_add_f32 v[26:27], v[26:27], v[30:31]
	v_pk_mul_f32 v[64:65], v[52:53], v[64:65]
	v_pk_mul_f32 v[66:67], v[54:55], v[66:67]
	v_pk_fma_f32 v[64:65], v[60:61], v[56:57], v[64:65]
	v_pk_fma_f32 v[66:67], v[62:63], v[58:59], v[66:67]
	v_pk_mul_f32 v[52:53], v[52:53], v[60:61]
	v_pk_mul_f32 v[54:55], v[54:55], v[62:63]
	v_pk_add_f32 v[44:45], v[44:45], v[64:65]
	v_pk_add_f32 v[46:47], v[46:47], v[66:67]
	v_pk_add_f32 v[48:49], v[48:49], v[52:53]
	v_pk_add_f32 v[50:51], v[50:51], v[54:55]
	v_pk_mul_f32 v[88:89], v[76:77], v[88:89]
	v_pk_mul_f32 v[90:91], v[78:79], v[90:91]
	v_pk_fma_f32 v[88:89], v[84:85], v[80:81], v[88:89]
	v_pk_fma_f32 v[90:91], v[86:87], v[82:83], v[90:91]
	v_pk_mul_f32 v[76:77], v[76:77], v[84:85]
	v_pk_mul_f32 v[78:79], v[78:79], v[86:87]
	v_pk_add_f32 v[68:69], v[68:69], v[88:89]
	v_pk_add_f32 v[70:71], v[70:71], v[90:91]
	v_pk_add_f32 v[72:73], v[72:73], v[76:77]
	v_pk_add_f32 v[74:75], v[74:75], v[78:79]
	v_pk_mul_f32 v[112:113], v[100:101], v[112:113]
	v_pk_mul_f32 v[114:115], v[102:103], v[114:115]
	v_pk_fma_f32 v[112:113], v[108:109], v[104:105], v[112:113]
	v_pk_fma_f32 v[114:115], v[110:111], v[106:107], v[114:115]
	v_pk_mul_f32 v[100:101], v[100:101], v[108:109]
	v_pk_mul_f32 v[102:103], v[102:103], v[110:111]
	v_pk_add_f32 v[92:93], v[92:93], v[112:113]
	v_pk_add_f32 v[94:95], v[94:95], v[114:115]
	v_pk_add_f32 v[96:97], v[96:97], v[100:101]
	v_pk_add_f32 v[98:99], v[98:99], v[102:103]
	s_andn2_b64 vcc, exec, s[26:27]
	s_cbranch_vccnz .Lfx0_nohalo
; __device__ __forceinline__ unsigned cvt_pk_bf16(float lo, float hi) { unsigned r; asm volatile("v_cvt_pk_bf16_f32 %0, %1, %2" : "=v"(r) : "v"(lo), "v"(hi)); return r; }
; __device__ __forceinline__ float silu_f(float g) { return g * __builtin_amdgcn_rcpf(1.0f + __builtin_amdgcn_exp2f(-1.44269504089f * g)); }
; template <int MODE>
; __device__ void fixup_tile(int pm, const float* cw, int C, int voff, int nch, const float* PART, const float* TAIL, bf16_t* O, int ldo, const bf16_t* BG) {
;     ...
;             if ((pm & 63) != 0) {
;                 const f32x4 t1 = *(const f32x4*)(TAIL + (size_t)((pm - 1) * 2 + 1) * C + co);
;                 const f32x4 w0 = *(const f32x4*)(cw + co);
;                 if (r == 0) { const f32x4 t2 = *(const f32x4*)(TAIL + (size_t)((pm - 1) * 2 + 0) * C + co); const f32x4 w1 = *(const f32x4*)(cw + C + co); a += w1 * t1 + w0 * t2; }
;                 else a += w0 * t1;
;             }
;             val[s] = a;
;         }
;         f32x4 o;
;         if (MODE == 0) {
; #pragma unroll
;             for (int j = 0; j < 4; ++j) o[j] = pg8::silu_f(val[0][j]) * val[1][j];
;         } else {
;             const u32x2 bg = *(const u32x2*)(BG + row * D + ch);
;             o[0] = __uint_as_float(bg.x << 16) * val[0][0]; o[1] = __uint_as_float(bg.x & 0xffff0000u) * val[0][1];
;             o[2] = __uint_as_float(bg.y << 16) * val[0][2]; o[3] = __uint_as_float(bg.y & 0xffff0000u) * val[0][3];
;         }
;         u32x2 w; w.x = cvt_pk_bf16(o[0], o[1]); w.y = cvt_pk_bf16(o[2], o[3]);
;         *(u32x2*)(O + img_off((int)row, ch, ldo)) = w;
	v_pk_mul_f32 v[136:137], v[124:125], v[136:137]
	v_pk_mul_f32 v[138:139], v[126:127], v[138:139]
	v_pk_fma_f32 v[136:137], v[132:133], v[128:129], v[136:137]
	v_pk_fma_f32 v[138:139], v[134:135], v[130:131], v[138:139]
	v_pk_mul_f32 v[124:125], v[124:125], v[132:133]
	v_pk_mul_f32 v[126:127], v[126:127], v[134:135]
	v_pk_add_f32 v[116:117], v[116:117], v[136:137]
	v_pk_add_f32 v[118:119], v[118:119], v[138:139]
	v_pk_add_f32 v[120:121], v[120:121], v[124:125]
	v_pk_add_f32 v[122:123], v[122:123], v[126:127]
	v_pk_mul_f32 v[160:161], v[148:149], v[160:161]
	v_pk_mul_f32 v[162:163], v[150:151], v[162:163]
	v_pk_fma_f32 v[160:161], v[156:157], v[152:153], v[160:161]
	v_pk_fma_f32 v[162:163], v[158:159], v[154:155], v[162:163]
	v_pk_mul_f32 v[148:149], v[148:149], v[156:157]
	v_pk_mul_f32 v[150:151], v[150:151], v[158:159]
	v_pk_add_f32 v[140:141], v[140:141], v[160:161]
	v_pk_add_f32 v[142:143], v[142:143], v[162:163]
	v_pk_add_f32 v[144:145], v[144:145], v[148:149]
	v_pk_add_f32 v[146:147], v[146:147], v[150:151]
.Lfx0_nohalo:
	v_mul_f32_e32 v170, 0xbfb8aa3b, v20
	v_mul_f32_e32 v171, 0xbfb8aa3b, v21
	v_mul_f32_e32 v172, 0xbfb8aa3b, v22
	v_mul_f32_e32 v173, 0xbfb8aa3b, v23
	v_exp_f32_e32 v170, v170
	v_exp_f32_e32 v171, v171
	v_exp_f32_e32 v172, v172
	v_exp_f32_e32 v173, v173
	v_add_f32_e32 v170, 1.0, v170
	v_add_f32_e32 v171, 1.0, v171
	v_add_f32_e32 v172, 1.0, v172
	v_add_f32_e32 v173, 1.0, v173
	v_rcp_f32_e32 v170, v170
	v_rcp_f32_e32 v171, v171
	v_rcp_f32_e32 v172, v172
	v_rcp_f32_e32 v173, v173
	v_mul_f32_e32 v20, v20, v170
	v_mul_f32_e32 v21, v21, v171
	v_mul_f32_e32 v22, v22, v172
	v_mul_f32_e32 v23, v23, v173
	v_mul_f32_e32 v20, v20, v44
	v_mul_f32_e32 v21, v21, v45
	v_mul_f32_e32 v22, v22, v46
	v_mul_f32_e32 v23, v23, v47
	v_cvt_pk_bf16_f32 v174, v20, v21
	v_cvt_pk_bf16_f32 v175, v22, v23
	global_store_dwordx2 v164, v[174:175], s[68:69]
	v_mul_f32_e32 v170, 0xbfb8aa3b, v24
	v_mul_f32_e32 v171, 0xbfb8aa3b, v25
	v_mul_f32_e32 v172, 0xbfb8aa3b, v26
	v_mul_f32_e32 v173, 0xbfb8aa3b, v27
	v_exp_f32_e32 v170, v170
	v_exp_f32_e32 v171, v171
	v_exp_f32_e32 v172, v172
	v_exp_f32_e32 v173, v173
	v_add_f32_e32 v170, 1.0, v170
	v_add_f32_e32 v171, 1.0, v171
	v_add_f32_e32 v172, 1.0, v172
	v_add_f32_e32 v173, 1.0, v173
	v_rcp_f32_e32 v170, v170
	v_rcp_f32_e32 v171, v171
	v_rcp_f32_e32 v172, v172
	v_rcp_f32_e32 v173, v173
	v_mul_f32_e32 v24, v24, v170
	v_mul_f32_e32 v25, v25, v171
	v_mul_f32_e32 v26, v26, v172
	v_mul_f32_e32 v27, v27, v173
	v_mul_f32_e32 v24, v24, v48
	v_mul_f32_e32 v25, v25, v49
	v_mul_f32_e32 v26, v26, v50
	v_mul_f32_e32 v27, v27, v51
	v_cvt_pk_bf16_f32 v176, v24, v25
	v_cvt_pk_bf16_f32 v177, v26, v27
	global_store_dwordx2 v164, v[176:177], s[68:69] offset:64
	v_mul_f32_e32 v170, 0xbfb8aa3b, v68
	v_mul_f32_e32 v171, 0xbfb8aa3b, v69
	v_mul_f32_e32 v172, 0xbfb8aa3b, v70
	v_mul_f32_e32 v173, 0xbfb8aa3b, v71
	v_exp_f32_e32 v170, v170
	v_exp_f32_e32 v171, v171
	v_exp_f32_e32 v172, v172
	v_exp_f32_e32 v173, v173
	v_add_f32_e32 v170, 1.0, v170
	v_add_f32_e32 v171, 1.0, v171
	v_add_f32_e32 v172, 1.0, v172
	v_add_f32_e32 v173, 1.0, v173
	v_rcp_f32_e32 v170, v170
	v_rcp_f32_e32 v171, v171
	v_rcp_f32_e32 v172, v172
	v_rcp_f32_e32 v173, v173
	v_mul_f32_e32 v68, v68, v170
	v_mul_f32_e32 v69, v69, v171
	v_mul_f32_e32 v70, v70, v172
	v_mul_f32_e32 v71, v71, v173
	v_mul_f32_e32 v68, v68, v92
	v_mul_f32_e32 v69, v69, v93
	v_mul_f32_e32 v70, v70, v94
	v_mul_f32_e32 v71, v71, v95
	v_cvt_pk_bf16_f32 v178, v68, v69
	v_cvt_pk_bf16_f32 v179, v70, v71
	global_store_dwordx2 v165, v[178:179], s[68:69]
	v_mul_f32_e32 v170, 0xbfb8aa3b, v72
	v_mul_f32_e32 v171, 0xbfb8aa3b, v73
	v_mul_f32_e32 v172, 0xbfb8aa3b, v74
	v_mul_f32_e32 v173, 0xbfb8aa3b, v75
	v_exp_f32_e32 v170, v170
	v_exp_f32_e32 v171, v171
	v_exp_f32_e32 v172, v172
	v_exp_f32_e32 v173, v173
	v_add_f32_e32 v170, 1.0, v170
	v_add_f32_e32 v171, 1.0, v171
	v_add_f32_e32 v172, 1.0, v172
	v_add_f32_e32 v173, 1.0, v173
	v_rcp_f32_e32 v170, v170
	v_rcp_f32_e32 v171, v171
	v_rcp_f32_e32 v172, v172
	v_rcp_f32_e32 v173, v173
	v_mul_f32_e32 v72, v72, v170
	v_mul_f32_e32 v73, v73, v171
	v_mul_f32_e32 v74, v74, v172
	v_mul_f32_e32 v75, v75, v173
	v_mul_f32_e32 v72, v72, v96
	v_mul_f32_e32 v73, v73, v97
	v_mul_f32_e32 v74, v74, v98
	v_mul_f32_e32 v75, v75, v99
	v_cvt_pk_bf16_f32 v180, v72, v73
	v_cvt_pk_bf16_f32 v181, v74, v75
	global_store_dwordx2 v165, v[180:181], s[68:69] offset:64
	s_andn2_b64 vcc, exec, s[26:27]
	s_cbranch_vccnz .LBB0_822
	v_mul_f32_e32 v170, 0xbfb8aa3b, v116
	v_mul_f32_e32 v171, 0xbfb8aa3b, v117
	v_mul_f32_e32 v172, 0xbfb8aa3b, v118
	v_mul_f32_e32 v173, 0xbfb8aa3b, v119
	v_exp_f32_e32 v170, v170
	v_exp_f32_e32 v171, v171
	v_exp_f32_e32 v172, v172
	v_exp_f32_e32 v173, v173
	v_add_f32_e32 v170, 1.0, v170
	v_add_f32_e32 v171, 1.0, v171
	v_add_f32_e32 v172, 1.0, v172
	v_add_f32_e32 v173, 1.0, v173
	v_rcp_f32_e32 v170, v170
	v_rcp_f32_e32 v171, v171
	v_rcp_f32_e32 v172, v172
	v_rcp_f32_e32 v173, v173
	v_mul_f32_e32 v116, v116, v170
	v_mul_f32_e32 v117, v117, v171
	v_mul_f32_e32 v118, v118, v172
	v_mul_f32_e32 v119, v119, v173
	v_mul_f32_e32 v116, v116, v140
	v_mul_f32_e32 v117, v117, v141
	v_mul_f32_e32 v118, v118, v142
	v_mul_f32_e32 v119, v119, v143
	v_cvt_pk_bf16_f32 v182, v116, v117
	v_cvt_pk_bf16_f32 v183, v118, v119
	global_store_dwordx2 v166, v[182:183], s[68:69]
	v_mul_f32_e32 v170, 0xbfb8aa3b, v120
	v_mul_f32_e32 v171, 0xbfb8aa3b, v121
	v_mul_f32_e32 v172, 0xbfb8aa3b, v122
	v_mul_f32_e32 v173, 0xbfb8aa3b, v123
	v_exp_f32_e32 v170, v170
	v_exp_f32_e32 v171, v171
	v_exp_f32_e32 v172, v172
	v_exp_f32_e32 v173, v173
	v_add_f32_e32 v170, 1.0, v170
	v_add_f32_e32 v171, 1.0, v171
	v_add_f32_e32 v172, 1.0, v172
	v_add_f32_e32 v173, 1.0, v173
	v_rcp_f32_e32 v170, v170
	v_rcp_f32_e32 v171, v171
	v_rcp_f32_e32 v172, v172
	v_rcp_f32_e32 v173, v173
	v_mul_f32_e32 v120, v120, v170
	v_mul_f32_e32 v121, v121, v171
	v_mul_f32_e32 v122, v122, v172
	v_mul_f32_e32 v123, v123, v173
	v_mul_f32_e32 v120, v120, v144
	v_mul_f32_e32 v121, v121, v145
	v_mul_f32_e32 v122, v122, v146
	v_mul_f32_e32 v123, v123, v147
	v_cvt_pk_bf16_f32 v184, v120, v121
	v_cvt_pk_bf16_f32 v185, v122, v123
	global_store_dwordx2 v166, v[184:185], s[68:69] offset:64
	s_branch .LBB0_822
